# v43 plus attention-B unit prologue: two of three serialized rotary-table load groups issued with the first
# speedup vs baseline: 1.0181x; 1.0012x over previous
; template <bool AXIAL>
; __device__ __forceinline__ void q_prep(bf16x8 (&qr)[8], const float* __restrict__ g, const int t, const int hi, const float* __restrict__ inv64, i32x8* qf = nullptr) {
;     ...
;   for (int d0 = 0; d0 < 8; ++d0) { const f32x4 g0 = *(const f32x4*)(g + d0 * 16 + hi * 8), g1 = *(const f32x4*)(g + d0 * 16 + hi * 8 + 4);
; #pragma unroll
;     for (int k = 0; k < 4; ++k) { x[d0][k] *= rs * g0[k]; x[d0][4 + k] *= rs * g1[k]; } }
; #pragma unroll
;   for (int p = 0; p < 4; ++p) {
;     const int da = AXIAL ? (p >> 1) * 4 + (p & 1) : p, db = AXIAL ? da + 2 : da + 4;
;     const float pos = AXIAL ? (float)((p >> 1) ? (t & 63) : (t >> 6)) : (float)t;
; template <int LD> ...
;     ...
;   const int lane = fresh_lane(), tid = wv * 64 + lane;
;   const int rb = wv >> 1, kh = wv & 1, r32 = lane & 31, hi = lane >> 5;
;   char* V_lds = lds + DV_OFF; char* K_lds = lds + DK_OFF; char* PX = lds + DPX_OFF;
;   float* xl = (float*)(lds + DXL_OFF); float* xs = (float*)(lds + DXS_OFF);
;   f32x16 o[4] = {}; bf16x8 qr[8]; float lsum = 0.f;
;   const int vbase = (int)(uintptr_t)V_lds + kh * 16384 + v_rd_base(lane);
;   const int vbo = vbase + kh * 8192, vbt = vbase + (1 - kh) * 8192;
;   const int krow = (kh * 32 + r32);
;   const int pxw = wv * 2048 + lane * 16, pxr = (wv ^ 1) * 2048 + lane * 16;
;   const int krl = lane >> 4;
;   const unsigned kof0 = (unsigned)((8 * wv + krl) * LD + (((lane & 15) ^ krl) * 8)) * 2u;
;   const unsigned kof1 = (unsigned)((8 * wv + 4 + krl) * LD + (((lane & 15) ^ (4 + krl)) * 8)) * 2u;
;   const int keyv = wv * 8 + ((lane & 31) >> 2);
;   const unsigned vof = (unsigned)(keyv * LD + (lane >> 5) * 32 + (lane & 3) * 8) * 2u;
;   LAS unsigned char* ldl = (LAS unsigned char*)lds;
;     ...
;   f32x16 pA, pB, pinit; bf16x8 ownA0, ownA1, ownB0, ownB1, ot0, ot1, kf[8]; s16x4 trA[8], trB[8]; const int NT = seq / KVBLK;
;   { float nb_ = nbC; asm volatile("" : "+v"(nb_));
; #pragma unroll
;     for (int r = 0; r < 16; ++r) pinit[r] = nb_; }
;   asm volatile("" : "+v"(pinit));
;   const int kb0 = (int)(uintptr_t)K_lds, pxra = (int)(uintptr_t)PX + pxr;
;   int v0 = 0, v1 = 32768, v2 = 65536;
;   DMA_TILE(0, 0, 0); DMA_TILE(1, 1, 32768);
;   { const bf16_t* Qw = Qb + (unsigned)((rb * QBLK + r32) * LD + hi * 8);
;     _Pragma("unroll")
;     for (int d0 = 0; d0 < 8; ++d0) qr[d0] = ld8(Qw + d0 * 16);
;     q_prep<false>(qr, qg, t0 + rb * QBLK + r32, hi, inv64); }
.LBB0_21:
	v_mbcnt_lo_u32_b32 v150, -1, 0
	v_mbcnt_hi_u32_b32 v150, -1, v150
	s_or_b32 s78, s24, s18
	v_lshlrev_b32_e32 v1, 1, v150
	v_lshlrev_b32_e32 v0, 3, v150
	v_lshlrev_b32_e32 v222, 4, v150
	v_and_b32_e32 v1, 32, v1
	s_xor_b64 s[2:3], s[52:53], -1
	s_lshl_b64 s[26:27], s[78:79], 1
	v_and_b32_e32 v218, 24, v0
	v_and_or_b32 v1, v222, s67, v1
	v_and_b32_e32 v0, 0x100, v0
	v_ashrrev_i32_e32 v213, 4, v150
	s_add_u32 vcc_lo, s58, s26
	v_or3_b32 v1, v1, v0, v218
	v_add_u32_e32 v0, 4, v213
	v_bfe_u32 v219, v150, 2, 3
	s_addc_u32 vcc_hi, s74, s27
	v_bitop3_b32 v3, v150, v213, 15 bitop3:0x6c
	v_bitop3_b32 v5, v0, v150, 15 bitop3:0x78
	v_mov_b32_e32 v254, s59
	v_and_b32_e32 v254, 8, v254
	v_xor_b32_e32 v3, v3, v254
	v_xor_b32_e32 v5, v5, v254
	v_or_b32_e32 v0, s59, v219
	v_and_b32_e32 v220, 0x7fffffe0, v150
	s_add_u32 s52, s19, s26
	v_add_u32_e32 v2, s59, v213
	v_lshl_add_u32 v0, v0, 13, v220
	v_mov_b32_e32 v64, v211
	v_add_u32_e32 v6, s14, v1
	v_lshlrev_b32_e32 v1, 4, v3
	s_addc_u32 s53, s75, s27
	v_add_u32_e32 v4, s60, v213
	v_or_b32_e32 v0, v0, v218
	v_lshl_add_u32 v160, v2, 14, v1
	v_lshlrev_b32_e32 v221, 4, v5
	v_mov_b32_e32 v65, v64
	v_mov_b32_e32 v66, v64
	v_mov_b32_e32 v67, v64
	v_mov_b32_e32 v68, v64
	v_mov_b32_e32 v69, v64
	v_mov_b32_e32 v70, v64
	v_mov_b32_e32 v71, v64
	v_mov_b32_e32 v72, v64
	v_mov_b32_e32 v73, v64
	v_mov_b32_e32 v74, v64
	v_mov_b32_e32 v75, v64
	v_mov_b32_e32 v76, v64
	v_mov_b32_e32 v77, v64
	v_mov_b32_e32 v78, v64
	v_mov_b32_e32 v79, v64
	s_mov_b32 m0, s76
	v_lshlrev_b32_e32 v0, 1, v0
	v_lshl_add_u32 v7, v4, 14, v221
	global_load_lds_dwordx4 v160, s[52:53]
	s_mov_b32 m0, s77
	v_mov_b32_e32 v1, v161
	global_load_lds_dwordx4 v7, s[52:53]
	v_lshl_add_u64 v[2:3], s[4:5], 0, v[0:1]
	s_mov_b32 m0, s62
	v_lshl_add_u64 v[4:5], v[2:3], 0, s[82:83]
	global_load_lds_dwordx4 v0, s[4:5]
	s_add_i32 m0, s62, 0x400
	v_and_b32_e32 v215, 31, v150
	global_load_lds_dwordx4 v[4:5], off
	v_lshl_add_u64 v[4:5], v[2:3], 0, s[84:85]
	s_add_i32 m0, s62, 0x4000
	v_lshl_add_u64 v[2:3], v[2:3], 0, s[86:87]
	global_load_lds_dwordx4 v[4:5], off
	s_add_i32 m0, s62, 0x4400
	s_add_u32 s26, s52, 0x100000
	global_load_lds_dwordx4 v[2:3], off
	s_addc_u32 s27, s53, 0
	s_mov_b32 m0, s6
	v_lshl_add_u64 v[2:3], s[80:81], 0, v[0:1]
	global_load_lds_dwordx4 v160, s[26:27]
	s_mov_b32 m0, s7
	v_ashrrev_i32_e32 v216, 5, v150
	global_load_lds_dwordx4 v7, s[26:27]
	s_add_i32 m0, s62, 0x8000
	v_or_b32_e32 v114, s98, v215
	global_load_lds_dwordx4 v0, s[80:81]
	v_lshl_add_u64 v[0:1], v[2:3], 0, s[82:83]
	s_add_i32 m0, s62, 0x8400
	v_add_u32_e32 v151, s34, v6
	global_load_lds_dwordx4 v[0:1], off
	v_lshl_add_u64 v[0:1], v[2:3], 0, s[84:85]
	s_add_i32 m0, s62, 0xc000
	v_add_u32_e32 v217, s99, v6
	global_load_lds_dwordx4 v[0:1], off
	v_lshl_add_u64 v[0:1], v[2:3], 0, s[86:87]
	s_add_i32 m0, s62, 0xc400
	v_mov_b32_e32 v3, v161
	global_load_lds_dwordx4 v[0:1], off
	v_or_b32_e32 v1, s36, v215
	v_lshlrev_b32_e32 v0, 3, v216
	v_lshl_add_u32 v2, v1, 13, v0
	v_ashrrev_i32_e32 v1, 31, v0
	v_lshlrev_b64 v[112:113], 2, v[0:1]
	s_getpc_b64 s[26:27]
	s_add_u32 s26, s26, _ZL9inv64_tab@rel32@lo+4
	s_addc_u32 s27, s27, _ZL9inv64_tab@rel32@hi+12
	v_lshl_add_u64 v[2:3], v[2:3], 1, vcc
	v_lshl_add_u64 v[0:1], s[0:1], 0, v[112:113]
	v_lshl_add_u64 v[118:119], s[26:27], 0, v[112:113]
	global_load_dwordx4 v[84:87], v[2:3], off
	global_load_dwordx4 v[88:91], v[2:3], off offset:32
	global_load_dwordx4 v[96:99], v[2:3], off offset:64
	global_load_dwordx4 v[104:107], v[2:3], off offset:96
	global_load_dwordx4 v[80:83], v[2:3], off offset:128
	global_load_dwordx4 v[92:95], v[2:3], off offset:160
	global_load_dwordx4 v[100:103], v[2:3], off offset:192
	global_load_dwordx4 v[108:111], v[2:3], off offset:224
	global_load_dwordx4 v[60:63], v[0:1], off
	global_load_dwordx4 v[56:59], v[0:1], off offset:16
	global_load_dwordx4 v[52:55], v[0:1], off offset:64
	global_load_dwordx4 v[48:51], v[0:1], off offset:80
	global_load_dwordx4 v[44:47], v[0:1], off offset:128
	global_load_dwordx4 v[40:43], v[0:1], off offset:144
	global_load_dwordx4 v[36:39], v[0:1], off offset:192
	global_load_dwordx4 v[32:35], v[0:1], off offset:208
	global_load_dwordx4 v[28:31], v[0:1], off offset:256
	global_load_dwordx4 v[24:27], v[0:1], off offset:272
	global_load_dwordx4 v[20:23], v[0:1], off offset:320
	global_load_dwordx4 v[16:19], v[0:1], off offset:336
	global_load_dwordx4 v[12:15], v[0:1], off offset:384
	global_load_dwordx4 v[8:11], v[0:1], off offset:400
	global_load_dwordx4 v[4:7], v[0:1], off offset:448
	s_nop 0
	global_load_dwordx4 v[0:3], v[0:1], off offset:464
	v_cvt_f32_i32_e32 v185, v114
	global_load_dwordx4 v[114:117], v[118:119], off offset:16
	global_load_dwordx4 v[120:123], v[118:119], off
	global_load_dwordx4 v[178:181], v[118:119], off offset:80
	global_load_dwordx4 v[136:139], v[118:119], off offset:64
	global_load_dwordx4 v[244:247], v[118:119], off offset:144
	global_load_dwordx4 v[156:159], v[118:119], off offset:128
	s_getpc_b64 s[26:27]
	s_add_u32 s26, s26, _ZL9inv64_tab@rel32@lo+68
	s_addc_u32 s27, s27, _ZL9inv64_tab@rel32@hi+76
	v_and_b32_e32 v214, 15, v150
	s_mov_b32 s52, 0x8000
	s_mov_b32 s53, 2
	s_mov_b64 vcc, s[28:29]
	s_waitcnt vmcnt(0)
; __device__ __forceinline__ float bf2f(bf16_t b) { return __uint_as_float((unsigned)b << 16); }
; template <bool AXIAL>
; __device__ __forceinline__ void q_prep(bf16x8 (&qr)[8], const float* __restrict__ g, const int t, const int hi, const float* __restrict__ inv64, i32x8* qf = nullptr) {
;     ...
;   for (int d0 = 0; d0 < 8; ++d0)
; #pragma unroll
;     for (int k = 0; k < 8; ++k) { x[d0][k] = bf2f((bf16_t)qr[d0][k]); ss += x[d0][k] * x[d0][k]; }
;   { auto rr = __builtin_amdgcn_permlane32_swap(__float_as_uint(ss), __float_as_uint(ss), false, false); ss = __uint_as_float(rr[0]) + __uint_as_float(rr[1]); }
;   const float rs = __builtin_amdgcn_rsqf(ss * (1.f / 128.f) + EPS) * QS;
; #pragma unroll
;   for (int d0 = 0; d0 < 8; ++d0) { const f32x4 g0 = *(const f32x4*)(g + d0 * 16 + hi * 8), g1 = *(const f32x4*)(g + d0 * 16 + hi * 8 + 4);
; #pragma unroll
;     for (int k = 0; k < 4; ++k) { x[d0][k] *= rs * g0[k]; x[d0][4 + k] *= rs * g1[k]; } }
; #pragma unroll
;   for (int p = 0; p < 4; ++p) {
;     const int da = AXIAL ? (p >> 1) * 4 + (p & 1) : p, db = AXIAL ? da + 2 : da + 4;
;     const float pos = AXIAL ? (float)((p >> 1) ? (t & 63) : (t >> 6)) : (float)t;
; #pragma unroll
;     for (int k = 0; k < 8; ++k) {
;       const int j = AXIAL ? 2 * ((p & 1) * 16 + hi * 8 + k) : p * 16 + hi * 8 + k;
;       const float rev = __builtin_amdgcn_fractf(pos * (inv64[j] * INV2PI));
;       const float c = __builtin_amdgcn_cosf(rev), s = __builtin_amdgcn_sinf(rev);
	v_and_b32_e32 v237, 0xffff0000, v85
	v_lshlrev_b32_e32 v236, 16, v85
	v_and_b32_e32 v85, 0xffff0000, v84
	v_lshlrev_b32_e32 v84, 16, v84
	v_mul_f32_e32 v240, v85, v85
	v_pk_fma_f32 v[240:241], v[84:85], v[84:85], v[240:241] op_sel_hi:[1,1,0]
	v_mul_f32_e32 v242, v237, v237
	v_pk_fma_f32 v[240:241], v[236:237], v[236:237], v[240:241]
	v_and_b32_e32 v233, 0xffff0000, v87
	v_mul_f32_e32 v114, 0.15915494, v114
	v_mul_f32_e32 v118, 0.15915494, v120
	v_mul_f32_e32 v118, v118, v185
	v_fract_f32_e32 v118, v118
	v_mul_f32_e32 v114, v114, v185
	v_cos_f32_e32 v120, v118
	v_sin_f32_e32 v124, v118
	v_mul_f32_e32 v118, 0.15915494, v121
	v_fract_f32_e32 v114, v114
	v_mul_f32_e32 v118, v118, v185
	v_cos_f32_e32 v126, v114
	v_sin_f32_e32 v132, v114
	v_mul_f32_e32 v114, 0.15915494, v115
	v_fract_f32_e32 v118, v118
	v_mul_f32_e32 v114, v114, v185
	v_cos_f32_e32 v121, v118
	v_sin_f32_e32 v125, v118
	v_mul_f32_e32 v118, 0.15915494, v122
	v_fract_f32_e32 v114, v114
	v_mul_f32_e32 v118, v118, v185
	v_cos_f32_e32 v127, v114
	v_sin_f32_e32 v133, v114
	v_mul_f32_e32 v114, 0.15915494, v116
	v_fract_f32_e32 v118, v118
	v_mul_f32_e32 v114, v114, v185
	v_cos_f32_e32 v122, v118
	v_sin_f32_e32 v128, v118
	v_mul_f32_e32 v118, 0.15915494, v123
	v_fract_f32_e32 v114, v114
	v_mul_f32_e32 v118, v118, v185
	v_cos_f32_e32 v130, v114
	v_sin_f32_e32 v134, v114
	v_mul_f32_e32 v114, 0.15915494, v117
	v_fract_f32_e32 v118, v118
	v_mul_f32_e32 v114, v114, v185
	v_cos_f32_e32 v123, v118
	v_sin_f32_e32 v129, v118
	v_fract_f32_e32 v114, v114
	v_lshl_add_u64 v[118:119], s[26:27], 0, v[112:113]
	v_cos_f32_e32 v131, v114
	v_sin_f32_e32 v135, v114
	s_getpc_b64 s[26:27]
	s_add_u32 s26, s26, _ZL9inv64_tab@rel32@lo+132
	s_addc_u32 s27, s27, _ZL9inv64_tab@rel32@hi+140
	v_lshlrev_b32_e32 v232, 16, v87
	v_and_b32_e32 v87, 0xffff0000, v86
	v_lshlrev_b32_e32 v86, 16, v86
	v_pk_add_f32 v[240:241], v[242:243], v[240:241] op_sel_hi:[0,1]
	v_pk_fma_f32 v[240:241], v[86:87], v[86:87], v[240:241]
	v_mul_f32_e32 v242, v87, v87
	v_pk_add_f32 v[240:241], v[242:243], v[240:241] op_sel_hi:[0,1]
	v_pk_fma_f32 v[240:241], v[232:233], v[232:233], v[240:241]
	v_mul_f32_e32 v242, v233, v233
	v_and_b32_e32 v229, 0xffff0000, v89
	v_lshlrev_b32_e32 v228, 16, v89
	v_and_b32_e32 v89, 0xffff0000, v88
	v_lshlrev_b32_e32 v88, 16, v88
	v_pk_add_f32 v[240:241], v[242:243], v[240:241] op_sel_hi:[0,1]
	v_pk_fma_f32 v[240:241], v[88:89], v[88:89], v[240:241]
	v_mul_f32_e32 v242, v89, v89
	v_pk_add_f32 v[240:241], v[242:243], v[240:241] op_sel_hi:[0,1]
	v_pk_fma_f32 v[240:241], v[228:229], v[228:229], v[240:241]
	v_mul_f32_e32 v242, v229, v229
	v_and_b32_e32 v227, 0xffff0000, v91
	v_lshlrev_b32_e32 v226, 16, v91
	v_and_b32_e32 v91, 0xffff0000, v90
	v_lshlrev_b32_e32 v90, 16, v90
	v_pk_add_f32 v[240:241], v[242:243], v[240:241] op_sel_hi:[0,1]
	v_pk_fma_f32 v[240:241], v[90:91], v[90:91], v[240:241]
	v_mul_f32_e32 v242, v91, v91
	v_pk_add_f32 v[240:241], v[242:243], v[240:241] op_sel_hi:[0,1]
	v_pk_fma_f32 v[240:241], v[226:227], v[226:227], v[240:241]
	v_mul_f32_e32 v242, v227, v227
	v_and_b32_e32 v225, 0xffff0000, v96
	v_lshlrev_b32_e32 v224, 16, v96
	v_pk_add_f32 v[240:241], v[242:243], v[240:241] op_sel_hi:[0,1]
	v_pk_fma_f32 v[240:241], v[224:225], v[224:225], v[240:241]
	v_mul_f32_e32 v242, v225, v225
	v_and_b32_e32 v201, 0xffff0000, v97
	v_lshlrev_b32_e32 v200, 16, v97
	v_pk_add_f32 v[240:241], v[242:243], v[240:241] op_sel_hi:[0,1]
	v_pk_fma_f32 v[240:241], v[200:201], v[200:201], v[240:241]
	v_mul_f32_e32 v242, v201, v201
	v_and_b32_e32 v199, 0xffff0000, v98
	v_lshlrev_b32_e32 v198, 16, v98
	v_pk_add_f32 v[240:241], v[242:243], v[240:241] op_sel_hi:[0,1]
	v_pk_fma_f32 v[240:241], v[198:199], v[198:199], v[240:241]
	v_mul_f32_e32 v242, v199, v199
	v_and_b32_e32 v197, 0xffff0000, v99
	v_lshlrev_b32_e32 v196, 16, v99
	v_pk_add_f32 v[240:241], v[242:243], v[240:241] op_sel_hi:[0,1]
	v_pk_fma_f32 v[240:241], v[196:197], v[196:197], v[240:241]
	v_mul_f32_e32 v242, v197, v197
	v_and_b32_e32 v195, 0xffff0000, v104
	v_lshlrev_b32_e32 v194, 16, v104
	v_pk_add_f32 v[240:241], v[242:243], v[240:241] op_sel_hi:[0,1]
	v_pk_fma_f32 v[240:241], v[194:195], v[194:195], v[240:241]
	v_mul_f32_e32 v242, v195, v195
	v_and_b32_e32 v193, 0xffff0000, v105
	v_lshlrev_b32_e32 v192, 16, v105
	v_pk_add_f32 v[240:241], v[242:243], v[240:241] op_sel_hi:[0,1]
	v_pk_fma_f32 v[240:241], v[192:193], v[192:193], v[240:241]
	v_mul_f32_e32 v242, v193, v193
	v_and_b32_e32 v191, 0xffff0000, v106
	v_lshlrev_b32_e32 v190, 16, v106
	v_pk_add_f32 v[240:241], v[242:243], v[240:241] op_sel_hi:[0,1]
	v_pk_fma_f32 v[240:241], v[190:191], v[190:191], v[240:241]
	v_mul_f32_e32 v242, v191, v191
	v_and_b32_e32 v189, 0xffff0000, v107
	v_lshlrev_b32_e32 v188, 16, v107
	v_pk_add_f32 v[240:241], v[242:243], v[240:241] op_sel_hi:[0,1]
	v_pk_fma_f32 v[240:241], v[188:189], v[188:189], v[240:241]
	v_mul_f32_e32 v242, v189, v189
	v_and_b32_e32 v239, 0xffff0000, v81
	v_lshlrev_b32_e32 v238, 16, v81
	v_and_b32_e32 v81, 0xffff0000, v80
	v_lshlrev_b32_e32 v80, 16, v80
	v_pk_add_f32 v[240:241], v[242:243], v[240:241] op_sel_hi:[0,1]
	v_pk_fma_f32 v[240:241], v[80:81], v[80:81], v[240:241]
	v_mul_f32_e32 v242, v81, v81
	v_pk_add_f32 v[240:241], v[242:243], v[240:241] op_sel_hi:[0,1]
	s_waitcnt vmcnt(0)
; __device__ __forceinline__ float bf2f(bf16_t b) { return __uint_as_float((unsigned)b << 16); }
; #define WBAR(n) do { asm volatile("s_waitcnt vmcnt(" #n ") lgkmcnt(0)" ::: "memory"); __builtin_amdgcn_s_barrier(); asm volatile("" ::: "memory"); } while (0)
; #define WBAR(n) do { asm volatile("s_waitcnt vmcnt(" #n ") lgkmcnt(0)" ::: "memory"); __builtin_amdgcn_s_barrier(); asm volatile("" ::: "memory"); } while (0)
; template <bool AXIAL>
; __device__ __forceinline__ void q_prep(bf16x8 (&qr)[8], const float* __restrict__ g, const int t, const int hi, const float* __restrict__ inv64, i32x8* qf = nullptr) {
;     ...
;     for (int k = 0; k < 8; ++k) { x[d0][k] = bf2f((bf16_t)qr[d0][k]); ss += x[d0][k] * x[d0][k]; }
;   { auto rr = __builtin_amdgcn_permlane32_swap(__float_as_uint(ss), __float_as_uint(ss), false, false); ss = __uint_as_float(rr[0]) + __uint_as_float(rr[1]); }
;   const float rs = __builtin_amdgcn_rsqf(ss * (1.f / 128.f) + EPS) * QS;
; #pragma unroll
;   for (int d0 = 0; d0 < 8; ++d0) { const f32x4 g0 = *(const f32x4*)(g + d0 * 16 + hi * 8), g1 = *(const f32x4*)(g + d0 * 16 + hi * 8 + 4);
; #pragma unroll
;     for (int k = 0; k < 4; ++k) { x[d0][k] *= rs * g0[k]; x[d0][4 + k] *= rs * g1[k]; } }
; #pragma unroll
;   for (int p = 0; p < 4; ++p) {
;     const int da = AXIAL ? (p >> 1) * 4 + (p & 1) : p, db = AXIAL ? da + 2 : da + 4;
;     const float pos = AXIAL ? (float)((p >> 1) ? (t & 63) : (t >> 6)) : (float)t;
; #pragma unroll
;     for (int k = 0; k < 8; ++k) {
;       const int j = AXIAL ? 2 * ((p & 1) * 16 + hi * 8 + k) : p * 16 + hi * 8 + k;
;       const float rev = __builtin_amdgcn_fractf(pos * (inv64[j] * INV2PI));
;       const float c = __builtin_amdgcn_cosf(rev), s = __builtin_amdgcn_sinf(rev);
; template <int LD> ...
;     ...
;   WBAR(0);
	v_mul_f32_e32 v114, 0.15915494, v178
	v_mul_f32_e32 v118, 0.15915494, v136
	v_mul_f32_e32 v118, v118, v185
	v_fract_f32_e32 v118, v118
	v_mul_f32_e32 v114, v114, v185
	v_cos_f32_e32 v136, v118
	v_sin_f32_e32 v140, v118
	v_mul_f32_e32 v118, 0.15915494, v137
	v_fract_f32_e32 v114, v114
	v_mul_f32_e32 v118, v118, v185
	v_cos_f32_e32 v142, v114
	v_sin_f32_e32 v152, v114
	v_mul_f32_e32 v114, 0.15915494, v179
	v_fract_f32_e32 v118, v118
	v_mul_f32_e32 v114, v114, v185
	v_cos_f32_e32 v137, v118
	v_sin_f32_e32 v141, v118
	v_mul_f32_e32 v118, 0.15915494, v138
	v_fract_f32_e32 v114, v114
	v_mul_f32_e32 v118, v118, v185
	v_cos_f32_e32 v143, v114
	v_sin_f32_e32 v153, v114
	v_mul_f32_e32 v114, 0.15915494, v180
	v_fract_f32_e32 v118, v118
	v_mul_f32_e32 v114, v114, v185
	v_cos_f32_e32 v138, v118
	v_sin_f32_e32 v144, v118
	v_mul_f32_e32 v118, 0.15915494, v139
	v_fract_f32_e32 v114, v114
	v_mul_f32_e32 v118, v118, v185
	v_cos_f32_e32 v146, v114
	v_sin_f32_e32 v154, v114
	v_mul_f32_e32 v114, 0.15915494, v181
	v_fract_f32_e32 v118, v118
	v_mul_f32_e32 v114, v114, v185
	v_cos_f32_e32 v139, v118
	v_sin_f32_e32 v145, v118
	v_fract_f32_e32 v114, v114
	v_lshl_add_u64 v[118:119], s[26:27], 0, v[112:113]
	v_cos_f32_e32 v147, v114
	v_sin_f32_e32 v155, v114
	s_getpc_b64 s[26:27]
	s_add_u32 s26, s26, _ZL9inv64_tab@rel32@lo+196
	s_addc_u32 s27, s27, _ZL9inv64_tab@rel32@hi+204
	v_pk_fma_f32 v[240:241], v[238:239], v[238:239], v[240:241]
	v_mul_f32_e32 v242, v239, v239
	v_and_b32_e32 v235, 0xffff0000, v83
	v_lshlrev_b32_e32 v234, 16, v83
	v_and_b32_e32 v83, 0xffff0000, v82
	v_lshlrev_b32_e32 v82, 16, v82
	v_pk_add_f32 v[240:241], v[242:243], v[240:241] op_sel_hi:[0,1]
	v_pk_fma_f32 v[240:241], v[82:83], v[82:83], v[240:241]
	v_mul_f32_e32 v242, v83, v83
	v_pk_add_f32 v[240:241], v[242:243], v[240:241] op_sel_hi:[0,1]
	v_pk_fma_f32 v[240:241], v[234:235], v[234:235], v[240:241]
	v_mul_f32_e32 v242, v235, v235
	v_and_b32_e32 v231, 0xffff0000, v93
	v_lshlrev_b32_e32 v230, 16, v93
	v_and_b32_e32 v93, 0xffff0000, v92
	v_lshlrev_b32_e32 v92, 16, v92
	v_pk_add_f32 v[240:241], v[242:243], v[240:241] op_sel_hi:[0,1]
	v_pk_fma_f32 v[240:241], v[92:93], v[92:93], v[240:241]
	v_mul_f32_e32 v242, v93, v93
	v_pk_add_f32 v[240:241], v[242:243], v[240:241] op_sel_hi:[0,1]
	v_pk_fma_f32 v[240:241], v[230:231], v[230:231], v[240:241]
	v_mul_f32_e32 v242, v231, v231
	v_and_b32_e32 v187, 0xffff0000, v111
	v_lshlrev_b32_e32 v186, 16, v111
	v_and_b32_e32 v107, 0xffff0000, v110
	v_lshlrev_b32_e32 v106, 16, v110
	v_and_b32_e32 v111, 0xffff0000, v109
	v_lshlrev_b32_e32 v110, 16, v109
	v_and_b32_e32 v105, 0xffff0000, v108
	v_lshlrev_b32_e32 v104, 16, v108
	v_and_b32_e32 v109, 0xffff0000, v103
	v_lshlrev_b32_e32 v108, 16, v103
	v_and_b32_e32 v99, 0xffff0000, v102
	v_lshlrev_b32_e32 v98, 16, v102
	v_and_b32_e32 v103, 0xffff0000, v101
	v_lshlrev_b32_e32 v102, 16, v101
	v_and_b32_e32 v97, 0xffff0000, v100
	v_lshlrev_b32_e32 v96, 16, v100
	v_and_b32_e32 v101, 0xffff0000, v95
	v_lshlrev_b32_e32 v100, 16, v95
	v_and_b32_e32 v95, 0xffff0000, v94
	v_lshlrev_b32_e32 v94, 16, v94
	v_pk_add_f32 v[240:241], v[242:243], v[240:241] op_sel_hi:[0,1]
	v_pk_fma_f32 v[240:241], v[94:95], v[94:95], v[240:241]
	v_mul_f32_e32 v242, v95, v95
	v_pk_add_f32 v[240:241], v[242:243], v[240:241] op_sel_hi:[0,1]
	v_pk_fma_f32 v[240:241], v[100:101], v[100:101], v[240:241]
	v_mul_f32_e32 v242, v101, v101
	v_pk_add_f32 v[240:241], v[242:243], v[240:241] op_sel_hi:[0,1]
	v_pk_fma_f32 v[240:241], v[96:97], v[96:97], v[240:241]
	v_mul_f32_e32 v242, v97, v97
	v_pk_add_f32 v[240:241], v[242:243], v[240:241] op_sel_hi:[0,1]
	v_pk_fma_f32 v[240:241], v[102:103], v[102:103], v[240:241]
	v_mul_f32_e32 v242, v103, v103
	v_pk_add_f32 v[240:241], v[242:243], v[240:241] op_sel_hi:[0,1]
	v_pk_fma_f32 v[240:241], v[98:99], v[98:99], v[240:241]
	v_mul_f32_e32 v242, v99, v99
	v_pk_add_f32 v[240:241], v[242:243], v[240:241] op_sel_hi:[0,1]
	v_pk_fma_f32 v[240:241], v[108:109], v[108:109], v[240:241]
	v_mul_f32_e32 v242, v109, v109
	v_pk_add_f32 v[240:241], v[242:243], v[240:241] op_sel_hi:[0,1]
	v_pk_fma_f32 v[240:241], v[104:105], v[104:105], v[240:241]
	v_mul_f32_e32 v242, v105, v105
	v_pk_add_f32 v[240:241], v[242:243], v[240:241] op_sel_hi:[0,1]
	v_pk_fma_f32 v[240:241], v[110:111], v[110:111], v[240:241]
	v_mul_f32_e32 v242, v111, v111
	v_pk_add_f32 v[240:241], v[242:243], v[240:241] op_sel_hi:[0,1]
	v_pk_fma_f32 v[240:241], v[106:107], v[106:107], v[240:241]
	v_mul_f32_e32 v242, v107, v107
	v_pk_add_f32 v[240:241], v[242:243], v[240:241] op_sel_hi:[0,1]
	v_pk_fma_f32 v[240:241], v[186:187], v[186:187], v[240:241]
	v_mul_f32_e32 v242, v187, v187
	v_pk_add_f32 v[240:241], v[242:243], v[240:241] op_sel_hi:[0,1]
	v_mov_b32_e32 v223, v240
	s_nop 1
	v_permlane32_swap_b32_e32 v240, v223
	v_add_f32_e32 v223, v240, v223
	s_waitcnt vmcnt(0)
	v_mul_f32_e32 v114, 0.15915494, v244
	v_mul_f32_e32 v118, 0.15915494, v156
	v_mul_f32_e32 v118, v118, v185
	v_mul_f32_e32 v114, v114, v185
	v_fract_f32_e32 v118, v118
	v_fract_f32_e32 v114, v114
	v_cos_f32_e32 v156, v118
	v_sin_f32_e32 v166, v118
	v_mul_f32_e32 v118, 0.15915494, v157
	v_cos_f32_e32 v168, v114
	v_sin_f32_e32 v174, v114
	v_mul_f32_e32 v114, 0.15915494, v245
	v_mul_f32_e32 v118, v118, v185
	v_mul_f32_e32 v114, v114, v185
	v_fract_f32_e32 v118, v118
	v_fract_f32_e32 v114, v114
	v_cos_f32_e32 v157, v118
	v_sin_f32_e32 v167, v118
	v_mul_f32_e32 v118, 0.15915494, v158
	v_cos_f32_e32 v169, v114
	v_sin_f32_e32 v175, v114
	v_mul_f32_e32 v114, 0.15915494, v246
	v_mul_f32_e32 v118, v118, v185
	v_mul_f32_e32 v114, v114, v185
	v_fract_f32_e32 v118, v118
	v_fract_f32_e32 v114, v114
	v_cos_f32_e32 v158, v118
	v_sin_f32_e32 v170, v118
	v_mul_f32_e32 v118, 0.15915494, v159
	v_cos_f32_e32 v172, v114
	v_sin_f32_e32 v176, v114
	v_mul_f32_e32 v114, 0.15915494, v247
	v_mul_f32_e32 v118, v118, v185
	v_mul_f32_e32 v114, v114, v185
	v_fract_f32_e32 v118, v118
	v_fract_f32_e32 v114, v114
	v_lshl_add_u64 v[116:117], s[26:27], 0, v[112:113]
	v_cos_f32_e32 v159, v118
	v_sin_f32_e32 v171, v118
	v_cos_f32_e32 v173, v114
	v_sin_f32_e32 v177, v114
	global_load_dwordx4 v[112:115], v[116:117], off offset:16
	s_nop 0
	global_load_dwordx4 v[116:119], v[116:117], off
	v_fmamk_f32 v223, v223, 0x3c000000, v203
	v_rsq_f32_e32 v223, v223
	s_waitcnt vmcnt(0) lgkmcnt(0)
	s_barrier
; template <bool AXIAL>
; __device__ __forceinline__ void q_prep(bf16x8 (&qr)[8], const float* __restrict__ g, const int t, const int hi, const float* __restrict__ inv64, i32x8* qf = nullptr) {
;     ...
;   const float rs = __builtin_amdgcn_rsqf(ss * (1.f / 128.f) + EPS) * QS;
; #pragma unroll
;   for (int d0 = 0; d0 < 8; ++d0) { const f32x4 g0 = *(const f32x4*)(g + d0 * 16 + hi * 8), g1 = *(const f32x4*)(g + d0 * 16 + hi * 8 + 4);
; #pragma unroll
;     for (int k = 0; k < 4; ++k) { x[d0][k] *= rs * g0[k]; x[d0][4 + k] *= rs * g1[k]; } }
; #pragma unroll
;   for (int p = 0; p < 4; ++p) {
;     const int da = AXIAL ? (p >> 1) * 4 + (p & 1) : p, db = AXIAL ? da + 2 : da + 4;
;     const float pos = AXIAL ? (float)((p >> 1) ? (t & 63) : (t >> 6)) : (float)t;
; #pragma unroll
;     for (int k = 0; k < 8; ++k) {
;       const int j = AXIAL ? 2 * ((p & 1) * 16 + hi * 8 + k) : p * 16 + hi * 8 + k;
;       const float rev = __builtin_amdgcn_fractf(pos * (inv64[j] * INV2PI));
;       const float c = __builtin_amdgcn_cosf(rev), s = __builtin_amdgcn_sinf(rev);
;       const float a = x[da][k], b = x[db][k];
;       x[da][k] = a * c - b * s; x[db][k] = b * c + a * s; } }
	v_mul_f32_e32 v240, 0x3e0293ee, v223
	v_pk_mul_f32 v[28:29], v[240:241], v[28:29] op_sel_hi:[0,1]
	v_pk_mul_f32 v[60:61], v[60:61], v[240:241] op_sel_hi:[1,0]
	v_pk_mul_f32 v[28:29], v[28:29], v[80:81]
	v_pk_mul_f32 v[60:61], v[60:61], v[84:85]
	v_pk_mul_f32 v[30:31], v[240:241], v[30:31] op_sel_hi:[0,1]
	v_pk_mul_f32 v[80:81], v[28:29], v[124:125]
	v_pk_mul_f32 v[62:63], v[62:63], v[240:241] op_sel_hi:[1,0]
	v_pk_mul_f32 v[30:31], v[30:31], v[238:239]
	v_pk_fma_f32 v[80:81], v[60:61], v[120:121], v[80:81] neg_lo:[0,0,1] neg_hi:[0,0,1]
	v_pk_mul_f32 v[60:61], v[60:61], v[124:125]
	v_pk_mul_f32 v[62:63], v[62:63], v[236:237]
	v_pk_mul_f32 v[24:25], v[240:241], v[24:25] op_sel_hi:[0,1]
	v_pk_fma_f32 v[28:29], v[28:29], v[120:121], v[60:61]
	v_pk_mul_f32 v[60:61], v[30:31], v[128:129]
	v_pk_mul_f32 v[56:57], v[56:57], v[240:241] op_sel_hi:[1,0]
	v_pk_mul_f32 v[24:25], v[24:25], v[82:83]
	v_pk_fma_f32 v[60:61], v[62:63], v[122:123], v[60:61] neg_lo:[0,0,1] neg_hi:[0,0,1]
	v_pk_mul_f32 v[62:63], v[62:63], v[128:129]
	v_pk_mul_f32 v[56:57], v[56:57], v[86:87]
	v_pk_mul_f32 v[26:27], v[240:241], v[26:27] op_sel_hi:[0,1]
	v_pk_fma_f32 v[30:31], v[30:31], v[122:123], v[62:63]
	v_pk_mul_f32 v[62:63], v[24:25], v[132:133]
	v_pk_mul_f32 v[58:59], v[58:59], v[240:241] op_sel_hi:[1,0]
	v_pk_mul_f32 v[26:27], v[26:27], v[234:235]
	v_pk_fma_f32 v[62:63], v[56:57], v[126:127], v[62:63] neg_lo:[0,0,1] neg_hi:[0,0,1]
	v_pk_mul_f32 v[56:57], v[56:57], v[132:133]
	v_pk_mul_f32 v[58:59], v[58:59], v[232:233]
	v_pk_mul_f32 v[20:21], v[240:241], v[20:21] op_sel_hi:[0,1]
	v_pk_fma_f32 v[24:25], v[24:25], v[126:127], v[56:57]
	v_pk_mul_f32 v[56:57], v[26:27], v[134:135]
	v_pk_mul_f32 v[52:53], v[52:53], v[240:241] op_sel_hi:[1,0]
	v_pk_mul_f32 v[20:21], v[20:21], v[92:93]
	v_pk_fma_f32 v[56:57], v[58:59], v[130:131], v[56:57] neg_lo:[0,0,1] neg_hi:[0,0,1]
	v_pk_mul_f32 v[58:59], v[58:59], v[134:135]
	v_pk_mul_f32 v[52:53], v[52:53], v[88:89]
	v_pk_mul_f32 v[22:23], v[240:241], v[22:23] op_sel_hi:[0,1]
	v_pk_fma_f32 v[26:27], v[26:27], v[130:131], v[58:59]
	v_pk_mul_f32 v[58:59], v[20:21], v[140:141]
	v_pk_mul_f32 v[54:55], v[54:55], v[240:241] op_sel_hi:[1,0]
	v_pk_mul_f32 v[22:23], v[22:23], v[230:231]
	v_pk_fma_f32 v[58:59], v[52:53], v[136:137], v[58:59] neg_lo:[0,0,1] neg_hi:[0,0,1]
	v_pk_mul_f32 v[52:53], v[52:53], v[140:141]
	v_pk_mul_f32 v[54:55], v[54:55], v[228:229]
	v_pk_mul_f32 v[16:17], v[240:241], v[16:17] op_sel_hi:[0,1]
	v_pk_fma_f32 v[20:21], v[20:21], v[136:137], v[52:53]
	v_pk_mul_f32 v[52:53], v[22:23], v[144:145]
	v_pk_mul_f32 v[48:49], v[48:49], v[240:241] op_sel_hi:[1,0]
	v_pk_mul_f32 v[16:17], v[16:17], v[94:95]
	v_pk_fma_f32 v[52:53], v[54:55], v[138:139], v[52:53] neg_lo:[0,0,1] neg_hi:[0,0,1]
	v_pk_mul_f32 v[54:55], v[54:55], v[144:145]
	v_pk_mul_f32 v[48:49], v[48:49], v[90:91]
	v_pk_mul_f32 v[18:19], v[240:241], v[18:19] op_sel_hi:[0,1]
	v_pk_fma_f32 v[22:23], v[22:23], v[138:139], v[54:55]
	v_pk_mul_f32 v[54:55], v[16:17], v[152:153]
	v_pk_mul_f32 v[50:51], v[50:51], v[240:241] op_sel_hi:[1,0]
	v_pk_mul_f32 v[18:19], v[18:19], v[100:101]
	v_pk_fma_f32 v[54:55], v[48:49], v[142:143], v[54:55] neg_lo:[0,0,1] neg_hi:[0,0,1]
	v_pk_mul_f32 v[48:49], v[48:49], v[152:153]
	v_pk_mul_f32 v[50:51], v[50:51], v[226:227]
	v_pk_mul_f32 v[12:13], v[240:241], v[12:13] op_sel_hi:[0,1]
	v_pk_fma_f32 v[16:17], v[16:17], v[142:143], v[48:49]
	v_pk_mul_f32 v[48:49], v[18:19], v[154:155]
	v_pk_mul_f32 v[44:45], v[44:45], v[240:241] op_sel_hi:[1,0]
	v_pk_mul_f32 v[12:13], v[12:13], v[96:97]
	v_pk_fma_f32 v[48:49], v[50:51], v[146:147], v[48:49] neg_lo:[0,0,1] neg_hi:[0,0,1]
	v_pk_mul_f32 v[50:51], v[50:51], v[154:155]
	v_pk_mul_f32 v[44:45], v[44:45], v[224:225]
	v_pk_mul_f32 v[14:15], v[240:241], v[14:15] op_sel_hi:[0,1]
	v_pk_fma_f32 v[18:19], v[18:19], v[146:147], v[50:51]
	v_pk_mul_f32 v[50:51], v[12:13], v[166:167]
	v_pk_mul_f32 v[46:47], v[46:47], v[240:241] op_sel_hi:[1,0]
	v_pk_mul_f32 v[14:15], v[14:15], v[102:103]
	v_pk_fma_f32 v[50:51], v[44:45], v[156:157], v[50:51] neg_lo:[0,0,1] neg_hi:[0,0,1]
	s_waitcnt vmcnt(0)
	v_mul_f32_e32 v116, 0.15915494, v116
	v_mul_f32_e32 v117, 0.15915494, v117
	v_pk_mul_f32 v[44:45], v[44:45], v[166:167]
	v_mul_f32_e32 v116, v116, v185
	v_mul_f32_e32 v117, v117, v185
	v_pk_mul_f32 v[46:47], v[46:47], v[200:201]
	v_pk_mul_f32 v[8:9], v[240:241], v[8:9] op_sel_hi:[0,1]
	v_pk_fma_f32 v[12:13], v[12:13], v[156:157], v[44:45]
	v_pk_mul_f32 v[44:45], v[14:15], v[170:171]
	v_fract_f32_e32 v178, v116
	v_fract_f32_e32 v179, v117
	v_mul_f32_e32 v118, 0.15915494, v118
	v_mul_f32_e32 v119, 0.15915494, v119
	v_pk_mul_f32 v[40:41], v[240:241], v[40:41] op_sel_hi:[0,1]
	v_pk_mul_f32 v[8:9], v[8:9], v[98:99]
	v_pk_fma_f32 v[44:45], v[46:47], v[158:159], v[44:45] neg_lo:[0,0,1] neg_hi:[0,0,1]
	v_pk_mul_f32 v[46:47], v[46:47], v[170:171]
	v_cos_f32_e32 v116, v178
	v_sin_f32_e32 v178, v178
	v_cos_f32_e32 v117, v179
	v_sin_f32_e32 v179, v179
	v_mul_f32_e32 v118, v118, v185
	v_mul_f32_e32 v119, v119, v185
	v_pk_mul_f32 v[40:41], v[40:41], v[198:199]
	v_pk_mul_f32 v[10:11], v[240:241], v[10:11] op_sel_hi:[0,1]
	v_pk_fma_f32 v[14:15], v[14:15], v[158:159], v[46:47]
	v_pk_mul_f32 v[46:47], v[8:9], v[174:175]
	v_fract_f32_e32 v180, v118
	v_fract_f32_e32 v181, v119
	v_mul_f32_e32 v112, 0.15915494, v112
	v_mul_f32_e32 v113, 0.15915494, v113
	v_pk_mul_f32 v[42:43], v[240:241], v[42:43] op_sel_hi:[0,1]
	v_pk_mul_f32 v[10:11], v[10:11], v[108:109]
	v_pk_fma_f32 v[46:47], v[40:41], v[168:169], v[46:47] neg_lo:[0,0,1] neg_hi:[0,0,1]
	v_pk_mul_f32 v[40:41], v[40:41], v[174:175]
	v_cos_f32_e32 v118, v180
	v_sin_f32_e32 v180, v180
	v_cos_f32_e32 v119, v181
; __device__ __forceinline__ unsigned pk4_fp8(float a, float b, float c, float d) { int p = __builtin_amdgcn_cvt_pk_fp8_f32(a, b, 0, false); return (unsigned)__builtin_amdgcn_cvt_pk_fp8_f32(c, d, p, true); }
; __device__ __forceinline__ unsigned cvtpk2(float lo, float hi) { return __builtin_bit_cast(unsigned, __builtin_convertvector((f32x2){lo, hi}, bf16v2)); }
; #define WBAR(n) do { asm volatile("s_waitcnt vmcnt(" #n ") lgkmcnt(0)" ::: "memory"); __builtin_amdgcn_s_barrier(); asm volatile("" ::: "memory"); } while (0)
; #define EXPC(P, lo) do { _Pragma("unroll") for (int r = (lo); r < (lo) + 4; ++r) { P[r] = __builtin_amdgcn_exp2f(P[r]); lsum += P[r]; } } while (0)
; #define PKW(p, o0, o1, b) do { PK4(p, 0, o0); PK4(p, 8, o1); *(bf16x8*)(PX + (b) * 16384 + pxw) = o0; *(bf16x8*)(PX + (b) * 16384 + pxw + 1024) = o1; } while (0)
; #define KRD_LO(KB) do { kf[0] = lds_rd128<(KB) * 16384>(a0_); kf[1] = lds_rd128<(KB) * 16384>(a1_); kf[2] = lds_rd128<(KB) * 16384>(a2_); kf[3] = lds_rd128<(KB) * 16384>(a3_); } while (0)
; template <bool AXIAL>
; __device__ __forceinline__ void q_prep(bf16x8 (&qr)[8], const float* __restrict__ g, const int t, const int hi, const float* __restrict__ inv64, i32x8* qf = nullptr) {
;     ...
;       const float c = __builtin_amdgcn_cosf(rev), s = __builtin_amdgcn_sinf(rev);
;       const float a = x[da][k], b = x[db][k];
;       x[da][k] = a * c - b * s; x[db][k] = b * c + a * s; } }
;   if (qf) {
; #pragma unroll
;     for (int s = 0; s < 2; ++s)
; #pragma unroll
;       for (int c = 0; c < 4; ++c) { qf[s][2 * c] = (int)pk4_fp8(x[4 * s + c][0] * 8.f, x[4 * s + c][1] * 8.f, x[4 * s + c][2] * 8.f, x[4 * s + c][3] * 8.f);
;         qf[s][2 * c + 1] = (int)pk4_fp8(x[4 * s + c][4] * 8.f, x[4 * s + c][5] * 8.f, x[4 * s + c][6] * 8.f, x[4 * s + c][7] * 8.f); }
;     return; }
; #pragma unroll
;   for (int d0 = 0; d0 < 8; ++d0) { u32x4 w = {cvtpk2(x[d0][0], x[d0][1]), cvtpk2(x[d0][2], x[d0][3]), cvtpk2(x[d0][4], x[d0][5]), cvtpk2(x[d0][6], x[d0][7])}; qr[d0] = *reinterpret_cast<bf16x8*>(&w); }
; template <int LD> ...
;     ...
;   { KADDR(); KRD_LO(0); KRD_HI(0); QK1(pA, 0, 7); QK1(pA, 1, 6); QK1(pA, 2, 5); QK1(pA, 3, 4); QK1(pA, 4, 3); QK1(pA, 5, 2); QK1(pA, 6, 1); QK1(pA, 7, 0); }
;   EXPC(pA, 0); EXPC(pA, 4); EXPC(pA, 8); EXPC(pA, 12); PKW(pA, ownA0, ownA1, 0);
;   WBAR(0);
	v_sin_f32_e32 v181, v181
	v_mul_f32_e32 v112, v112, v185
	v_mul_f32_e32 v113, v113, v185
	v_pk_mul_f32 v[42:43], v[42:43], v[196:197]
	v_pk_mul_f32 v[4:5], v[240:241], v[4:5] op_sel_hi:[0,1]
	v_pk_fma_f32 v[8:9], v[8:9], v[168:169], v[40:41]
	v_pk_mul_f32 v[40:41], v[10:11], v[176:177]
	v_fract_f32_e32 v182, v112
	v_fract_f32_e32 v183, v113
	v_mul_f32_e32 v114, 0.15915494, v114
	v_mul_f32_e32 v115, 0.15915494, v115
	v_pk_mul_f32 v[36:37], v[240:241], v[36:37] op_sel_hi:[0,1]
	v_pk_mul_f32 v[4:5], v[4:5], v[104:105]
	v_pk_fma_f32 v[40:41], v[42:43], v[172:173], v[40:41] neg_lo:[0,0,1] neg_hi:[0,0,1]
	v_pk_mul_f32 v[42:43], v[42:43], v[176:177]
	v_cos_f32_e32 v112, v182
	v_sin_f32_e32 v182, v182
	v_cos_f32_e32 v113, v183
	v_sin_f32_e32 v183, v183
	v_mul_f32_e32 v114, v114, v185
	v_mul_f32_e32 v115, v115, v185
	v_pk_mul_f32 v[36:37], v[36:37], v[194:195]
	v_pk_mul_f32 v[6:7], v[240:241], v[6:7] op_sel_hi:[0,1]
	v_pk_fma_f32 v[10:11], v[10:11], v[172:173], v[42:43]
	v_pk_mul_f32 v[42:43], v[4:5], v[178:179]
	v_fract_f32_e32 v184, v114
	v_fract_f32_e32 v185, v115
	v_pk_mul_f32 v[38:39], v[240:241], v[38:39] op_sel_hi:[0,1]
	v_pk_mul_f32 v[6:7], v[6:7], v[110:111]
	v_pk_fma_f32 v[42:43], v[36:37], v[116:117], v[42:43] neg_lo:[0,0,1] neg_hi:[0,0,1]
	v_pk_mul_f32 v[36:37], v[36:37], v[178:179]
	v_cos_f32_e32 v114, v184
	v_sin_f32_e32 v184, v184
	v_cos_f32_e32 v115, v185
	v_sin_f32_e32 v185, v185
	v_pk_mul_f32 v[38:39], v[38:39], v[192:193]
	v_pk_mul_f32 v[0:1], v[240:241], v[0:1] op_sel_hi:[0,1]
	v_pk_fma_f32 v[4:5], v[4:5], v[116:117], v[36:37]
	v_pk_mul_f32 v[36:37], v[6:7], v[180:181]
	v_pk_mul_f32 v[32:33], v[240:241], v[32:33] op_sel_hi:[0,1]
	v_pk_mul_f32 v[0:1], v[0:1], v[106:107]
	v_pk_fma_f32 v[36:37], v[38:39], v[118:119], v[36:37] neg_lo:[0,0,1] neg_hi:[0,0,1]
	v_pk_mul_f32 v[38:39], v[38:39], v[180:181]
	v_pk_mul_f32 v[32:33], v[32:33], v[190:191]
	v_pk_mul_f32 v[2:3], v[240:241], v[2:3] op_sel_hi:[0,1]
	v_pk_fma_f32 v[6:7], v[6:7], v[118:119], v[38:39]
	v_pk_mul_f32 v[38:39], v[0:1], v[182:183]
	v_pk_mul_f32 v[34:35], v[240:241], v[34:35] op_sel_hi:[0,1]
	v_pk_mul_f32 v[2:3], v[2:3], v[186:187]
	v_pk_fma_f32 v[38:39], v[32:33], v[112:113], v[38:39] neg_lo:[0,0,1] neg_hi:[0,0,1]
	v_pk_mul_f32 v[32:33], v[32:33], v[182:183]
	v_pk_mul_f32 v[34:35], v[34:35], v[188:189]
	v_pk_fma_f32 v[0:1], v[0:1], v[112:113], v[32:33]
	v_pk_mul_f32 v[32:33], v[2:3], v[184:185]
	v_and_b32_e32 v172, 0xf0, v222
	v_pk_fma_f32 v[32:33], v[34:35], v[114:115], v[32:33] neg_lo:[0,0,1] neg_hi:[0,0,1]
	v_pk_mul_f32 v[34:35], v[34:35], v[184:185]
	v_cvt_pk_bf16_f32 v118, v0, v1
	v_mov_b32_e32 v0, v172
	v_lshl_add_u32 v173, v215, 8, s37
	v_lshlrev_b32_e32 v178, 4, v216
	v_pk_fma_f32 v[2:3], v[2:3], v[114:115], v[34:35]
	v_cvt_pk_bf16_f32 v106, v16, v17
	v_cvt_pk_bf16_f32 v107, v18, v19
	v_add_u32_e32 v174, 32, v178
	v_xad_u32 v1, v0, v178, v173
	ds_read_b128 v[16:19], v1 offset:0
	v_cvt_pk_bf16_f32 v104, v20, v21
	v_cvt_pk_bf16_f32 v105, v22, v23
	v_cvt_pk_bf16_f32 v119, v2, v3
	v_xad_u32 v2, v0, v174, v173
	v_add_u32_e32 v175, 64, v178
	ds_read_b128 v[20:23], v2 offset:0
	v_cvt_pk_bf16_f32 v98, v24, v25
	v_cvt_pk_bf16_f32 v99, v26, v27
	v_xad_u32 v3, v0, v175, v173
	v_add_u32_e32 v176, 0x60, v178
	ds_read_b128 v[24:27], v3 offset:0
	v_cvt_pk_bf16_f32 v96, v28, v29
	v_cvt_pk_bf16_f32 v97, v30, v31
	v_xad_u32 v0, v0, v176, v173
	ds_read_b128 v[28:31], v0 offset:0
	v_cvt_pk_bf16_f32 v103, v32, v33
	v_xor_b32_e32 v1, 0x80, v1
	ds_read_b128 v[32:35], v1 offset:0
	v_cvt_pk_bf16_f32 v101, v36, v37
	v_cvt_pk_bf16_f32 v102, v38, v39
	v_xor_b32_e32 v2, 0x80, v2
	ds_read_b128 v[36:39], v2 offset:0
	v_cvt_pk_bf16_f32 v115, v40, v41
	v_cvt_pk_bf16_f32 v100, v42, v43
	v_xor_b32_e32 v3, 0x80, v3
	ds_read_b128 v[40:43], v3 offset:0
	v_cvt_pk_bf16_f32 v120, v80, v81
	v_cvt_pk_bf16_f32 v121, v60, v61
	v_cvt_pk_bf16_f32 v122, v62, v63
	v_cvt_pk_bf16_f32 v123, v56, v57
	v_cvt_pk_bf16_f32 v113, v44, v45
	v_cvt_pk_bf16_f32 v114, v46, v47
	v_xor_b32_e32 v0, 0x80, v0
	ds_read_b128 v[44:47], v0 offset:0
	v_cvt_pk_bf16_f32 v108, v12, v13
	v_cvt_pk_bf16_f32 v109, v14, v15
	v_cvt_pk_bf16_f32 v110, v8, v9
	v_cvt_pk_bf16_f32 v111, v10, v11
	v_cvt_pk_bf16_f32 v116, v4, v5
	v_cvt_pk_bf16_f32 v117, v6, v7
	s_waitcnt lgkmcnt(7)
	v_cvt_pk_bf16_f32 v124, v58, v59
	v_mfma_f32_32x32x16_bf16 v[0:15], v[16:19], v[120:123], v[64:79]
	v_cvt_pk_bf16_f32 v125, v52, v53
	v_cvt_pk_bf16_f32 v126, v54, v55
	v_cvt_pk_bf16_f32 v127, v48, v49
	s_waitcnt lgkmcnt(6)
	v_cvt_pk_bf16_f32 v112, v50, v51
	s_waitcnt lgkmcnt(5)
	s_waitcnt lgkmcnt(4)
	s_waitcnt lgkmcnt(3)
	s_nop 0
	v_mfma_f32_32x32x16_bf16 v[0:15], v[20:23], v[124:127], v[0:15]
	s_waitcnt lgkmcnt(2)
	s_waitcnt lgkmcnt(1)
	s_waitcnt lgkmcnt(0)
	s_add_i32 s78, s18, s24
	s_lshl_b64 s[24:25], s[78:79], 1
	v_lshl_add_u64 v[152:153], s[24:25], 0, v[160:161]
	v_add_u32_e32 v171, s15, v222
	v_mfma_f32_32x32x16_bf16 v[0:15], v[24:27], v[112:115], v[0:15]
	s_mov_b32 s26, 0
	v_mfma_f32_32x32x16_bf16 v[0:15], v[28:31], v[100:103], v[0:15]
	v_mfma_f32_32x32x16_bf16 v[0:15], v[32:35], v[96:99], v[0:15]
	v_mfma_f32_32x32x16_bf16 v[0:15], v[36:39], v[104:107], v[0:15]
	v_mfma_f32_32x32x16_bf16 v[0:15], v[40:43], v[108:111], v[0:15]
	v_mfma_f32_32x32x16_bf16 v[0:15], v[44:47], v[116:119], v[0:15]
	s_nop 11
	v_exp_f32_e32 v16, v0
	v_exp_f32_e32 v1, v1
	v_exp_f32_e32 v2, v2
	v_exp_f32_e32 v3, v3
	v_exp_f32_e32 v4, v4
	v_cvt_pk_bf16_f32 v128, v16, v1
	v_add_f32_e32 v16, 0, v16
	v_exp_f32_e32 v5, v5
	v_add_f32_e32 v1, v1, v16
	v_exp_f32_e32 v6, v6
	v_add_f32_e32 v1, v2, v1
	v_exp_f32_e32 v7, v7
	v_add_f32_e32 v1, v3, v1
	v_exp_f32_e32 v8, v8
	v_add_f32_e32 v1, v4, v1
	v_exp_f32_e32 v9, v9
	v_add_f32_e32 v1, v5, v1
	v_exp_f32_e32 v10, v10
	v_add_f32_e32 v1, v6, v1
	v_exp_f32_e32 v11, v11
	v_add_f32_e32 v1, v7, v1
	v_exp_f32_e32 v12, v12
	v_add_f32_e32 v1, v8, v1
	v_exp_f32_e32 v13, v13
	v_add_f32_e32 v1, v9, v1
	v_exp_f32_e32 v14, v14
	v_add_f32_e32 v1, v10, v1
	v_exp_f32_e32 v15, v15
	v_add_f32_e32 v1, v11, v1
	v_add_f32_e32 v1, v12, v1
	v_add_u32_e32 v0, s35, v222
	v_add_f32_e32 v1, v13, v1
	v_add_u32_e32 v179, 0, v0
	v_add_f32_e32 v1, v14, v1
	v_cvt_pk_bf16_f32 v129, v2, v3
	v_cvt_pk_bf16_f32 v130, v4, v5
	v_cvt_pk_bf16_f32 v131, v6, v7
	v_add_u32_e32 v180, 0x20000, v179
	v_add_f32_e32 v170, v15, v1
	v_lshlrev_b32_e32 v1, 14, v213
	v_cvt_pk_bf16_f32 v132, v8, v9
	v_cvt_pk_bf16_f32 v133, v10, v11
	v_cvt_pk_bf16_f32 v134, v12, v13
	v_cvt_pk_bf16_f32 v135, v14, v15
	ds_write_b128 v180, v[128:131]
	ds_write_b128 v180, v[132:135] offset:1024
	v_add3_u32 v160, s44, v1, v221
	v_lshlrev_b32_e32 v1, 13, v219
	s_waitcnt vmcnt(0) lgkmcnt(0)
	s_barrier
; template <int LD> ...
;     ...
;   f32x16 o[4] = {}; bf16x8 qr[8]; float lsum = 0.f;
;     ...
;   for (int j = 1; j + 1 < NT; j += 2) {
	v_add3_u32 v1, s45, v1, v220
	v_mov_b32_e32 v0, 0
	v_lshl_add_u64 v[154:155], s[24:25], 0, v[160:161]
	v_add_lshl_u32 v160, v1, v218, 1
	v_lshl_add_u64 v[156:157], s[20:21], 0, v[160:161]
	s_mov_b32 s24, 0x10000
	v_mov_b32_e32 v1, v0
	v_mov_b32_e32 v2, v0
	v_mov_b32_e32 v3, v0
	v_mov_b32_e32 v4, v0
	v_mov_b32_e32 v5, v0
	v_mov_b32_e32 v6, v0
	v_mov_b32_e32 v7, v0
	v_mov_b32_e32 v8, v0
	v_mov_b32_e32 v9, v0
	v_mov_b32_e32 v10, v0
	v_mov_b32_e32 v11, v0
	v_mov_b32_e32 v12, v0
	v_mov_b32_e32 v13, v0
	v_mov_b32_e32 v14, v0
	v_mov_b32_e32 v15, v0
	v_mov_b32_e32 v16, v0
	v_mov_b32_e32 v17, v0
	v_mov_b32_e32 v18, v0
	v_mov_b32_e32 v19, v0
	v_mov_b32_e32 v20, v0
	v_mov_b32_e32 v21, v0
	v_mov_b32_e32 v22, v0
	v_mov_b32_e32 v23, v0
	v_mov_b32_e32 v24, v0
	v_mov_b32_e32 v25, v0
	v_mov_b32_e32 v26, v0
	v_mov_b32_e32 v27, v0
	v_mov_b32_e32 v28, v0
	v_mov_b32_e32 v29, v0
	v_mov_b32_e32 v30, v0
	v_mov_b32_e32 v31, v0
	v_mov_b32_e32 v32, v0
	v_mov_b32_e32 v33, v0
	v_mov_b32_e32 v34, v0
	v_mov_b32_e32 v35, v0
	v_mov_b32_e32 v36, v0
	v_mov_b32_e32 v37, v0
	v_mov_b32_e32 v38, v0
	v_mov_b32_e32 v39, v0
	v_mov_b32_e32 v40, v0
	v_mov_b32_e32 v41, v0
	v_mov_b32_e32 v42, v0
	v_mov_b32_e32 v43, v0
	v_mov_b32_e32 v44, v0
	v_mov_b32_e32 v45, v0
	v_mov_b32_e32 v46, v0
	v_mov_b32_e32 v47, v0
	v_mov_b32_e32 v48, v0
	v_mov_b32_e32 v49, v0
	v_mov_b32_e32 v50, v0
	v_mov_b32_e32 v51, v0
	v_mov_b32_e32 v52, v0
	v_mov_b32_e32 v53, v0
	v_mov_b32_e32 v54, v0
	v_mov_b32_e32 v55, v0
	v_mov_b32_e32 v56, v0
	v_mov_b32_e32 v57, v0
	v_mov_b32_e32 v58, v0
	v_mov_b32_e32 v59, v0
	v_mov_b32_e32 v60, v0
	v_mov_b32_e32 v61, v0
	v_mov_b32_e32 v62, v0
	v_mov_b32_e32 v63, v0
	v_readlane_b32 s27, v253, 3
	s_cmp_gt_u32 s27, 3
	s_cbranch_scc1 .Lb_loopY
